# y-row stores/atomics of the state chain: scalar base + one 32-bit offset per chunk and one v_mad per row instead of 16 64-bit address chains
# baseline (speedup 1.0000x reference)
.Le23_skip_b:
	s_waitcnt lgkmcnt(0)
	s_barrier
	s_andn2_b64 vcc, exec, s[8:9]
	s_cbranch_vccnz .LBB0_1106
	v_lshlrev_b32_e32 v80, 1, v0
	v_add_u32_e32 v46, v66, v80
	v_add_u32_e32 v47, 0x4000, v46
	ds_read2_b64 v[34:37], v47 offset0:32 offset1:34
	v_cvt_pk_bf16_f32 v38, v18, v19
	v_cvt_pk_bf16_f32 v39, v20, v21
	v_cvt_pk_bf16_f32 v40, v22, v23
	v_cvt_pk_bf16_f32 v41, v24, v25
	ds_read2_b64 v[42:45], v47 offset0:36 offset1:38
	v_lshlrev_b32_e32 v48, 3, v51
	v_cvt_pk_bf16_f32 v72, v26, v27
	v_cvt_pk_bf16_f32 v73, v28, v29
	s_waitcnt lgkmcnt(1)
	v_mfma_f32_32x32x16_bf16 v[50:65], v[34:37], v[38:41], 0
	v_cvt_pk_bf16_f32 v74, v30, v31
	v_cvt_pk_bf16_f32 v75, v32, v33
	ds_read2_b64 v[34:37], v47 offset0:40 offset1:42
	v_cvt_pk_bf16_f32 v76, v2, v3
	v_cvt_pk_bf16_f32 v77, v4, v5
	v_cvt_pk_bf16_f32 v78, v6, v7
	v_cvt_pk_bf16_f32 v79, v8, v9
	s_waitcnt lgkmcnt(1)
	v_mfma_f32_32x32x16_bf16 v[50:65], v[42:45], v[72:75], v[50:65]
	ds_read2_b64 v[42:45], v47 offset0:44 offset1:46
	v_cvt_pk_bf16_f32 v172, v10, v11
	v_cvt_pk_bf16_f32 v173, v12, v13
	v_cvt_pk_bf16_f32 v174, v14, v15
	v_cvt_pk_bf16_f32 v175, v16, v17
	v_mov_b32_e32 v49, s92
	v_bitop3_b32 v47, v48, v141, 24 bitop3:0x78
	s_waitcnt lgkmcnt(1)
	v_mfma_f32_32x32x16_bf16 v[50:65], v[34:37], v[76:79], v[50:65]
	v_lshlrev_b32_e32 v34, 6, v70
	v_sub_u32_e32 v177, v66, v34
	v_lshl_add_u32 v70, v48, 1, v177
	ds_read_b128 v[34:37], v70 offset:50624
	v_mad_u32_u24 v49, v71, s77, v49
	v_lshlrev_b32_e32 v207, 1, v47
	v_and_b32_e32 v145, 24, v141
	s_waitcnt lgkmcnt(1)
	v_mfma_f32_32x32x16_bf16 v[50:65], v[42:45], v[172:175], v[50:65]
	v_add_u32_e32 v42, v49, v207
	ds_read_b128 v[130:133], v42 offset:45440
	v_bitop3_b32 v67, v48, v145, 16 bitop3:0x36
	v_lshlrev_b32_e32 v212, 1, v67
	v_add_u32_e32 v71, 0x5000, v46
	v_add_u32_e32 v47, v49, v212
	ds_read_b128 v[42:45], v70 offset:50656
	ds_read_b128 v[126:129], v47 offset:45440
	s_waitcnt lgkmcnt(2)
	v_mfma_f32_32x32x16_bf16 v[50:65], v[34:37], v[130:133], v[50:65]
	ds_read2_b64 v[34:37], v71 offset0:96 offset1:98
	ds_read2_b64 v[66:69], v71 offset0:100 offset1:102
	ds_read2_b64 v[178:181], v71 offset0:104 offset1:106
	ds_read2_b64 v[182:185], v71 offset0:108 offset1:110
	ds_read_b128 v[186:189], v70 offset:55744
	ds_read_b128 v[190:193], v70 offset:55776
	v_lshlrev_b32_e32 v81, 2, v0
	s_sub_i32 s58, s93, 32
	s_add_i32 s59, s94, 32
	s_and_b64 s[12:13], s[10:11], exec
	s_waitcnt lgkmcnt(6)
	v_mfma_f32_32x32x16_bf16 v[50:65], v[42:45], v[126:129], v[50:65]
	s_cselect_b32 s12, s58, s59
	s_add_i32 s12, s12, s87
	s_waitcnt lgkmcnt(5)
	v_mfma_f32_32x32x16_bf16 v[34:49], v[34:37], v[38:41], 0
	s_nop 7
	v_cvt_pk_bf16_f32 v50, v50, v51
	v_cvt_pk_bf16_f32 v51, v52, v53
	v_cvt_pk_bf16_f32 v52, v54, v55
	v_cvt_pk_bf16_f32 v53, v56, v57
	s_waitcnt lgkmcnt(4)
	v_mfma_f32_32x32x16_bf16 v[34:49], v[66:69], v[72:75], v[34:49]
	ds_read_b128 v[66:69], v81 offset:60928
	ds_read_b128 v[70:73], v81 offset:60960
	ds_read_b128 v[194:197], v81 offset:60864
	ds_read_b128 v[198:201], v81 offset:60896
	ds_read_b128 v[202:205], v81 offset:60992
	ds_read_b128 v[208:211], v81 offset:61024
	s_waitcnt lgkmcnt(4)
	v_pk_mul_f32 v[30:31], v[30:31], v[70:71]
	v_pk_mul_f32 v[26:27], v[26:27], v[66:67]
	v_pk_mul_f32 v[32:33], v[32:33], v[72:73]
	v_pk_mul_f32 v[28:29], v[28:29], v[68:69]
	ds_read_b128 v[66:69], v81 offset:61056
	ds_read_b128 v[70:73], v81 offset:61088
	s_waitcnt lgkmcnt(4)
	v_pk_mul_f32 v[22:23], v[22:23], v[198:199]
	v_mfma_f32_32x32x16_bf16 v[34:49], v[178:181], v[76:79], v[34:49]
	v_mul_f32_e64 v24, v24, v200
	v_mul_f32_e64 v25, v25, v201
	s_waitcnt lgkmcnt(1)
	v_mul_f32_e64 v10, v10, v66
	v_mul_f32_e64 v11, v11, v67
	s_waitcnt lgkmcnt(0)
	v_pk_mul_f32 v[14:15], v[14:15], v[70:71]
	v_pk_mul_f32 v[16:17], v[16:17], v[72:73]
	v_pk_mul_f32 v[12:13], v[12:13], v[68:69]
	v_pk_mul_f32 v[20:21], v[20:21], v[196:197]
	v_pk_mul_f32 v[18:19], v[18:19], v[194:195]
	v_mfma_f32_32x32x16_bf16 v[34:49], v[182:185], v[172:175], v[34:49]
	v_add_u32_e32 v172, v177, v80
	v_add_u32_e32 v66, 0xe000, v172
	ds_read2_b64 v[74:77], v66 offset0:120 offset1:122
	ds_read2_b64 v[54:57], v66 offset0:124 offset1:126
	v_mul_f32_e64 v6, v6, v208
	v_mul_f32_e64 v7, v7, v209
	v_pk_mul_f32 v[8:9], v[8:9], v[210:211]
	v_pk_mul_f32 v[4:5], v[4:5], v[204:205]
	s_waitcnt lgkmcnt(1)
	v_mfma_f32_32x32x16_bf16 v[66:81], v[74:77], v[50:53], 0
	v_cvt_pk_bf16_f32 v50, v58, v59
	v_cvt_pk_bf16_f32 v51, v60, v61
	v_cvt_pk_bf16_f32 v52, v62, v63
	v_cvt_pk_bf16_f32 v53, v64, v65
	v_add_u32_e32 v62, v177, v212
	v_pk_mul_f32 v[2:3], v[2:3], v[202:203]
	s_waitcnt lgkmcnt(0)
	v_mfma_f32_32x32x16_bf16 v[66:81], v[54:57], v[50:53], v[66:81]
	v_add_u32_e32 v54, v177, v207
	ds_read_b128 v[50:53], v54 offset:40256
	ds_read_b128 v[54:57], v54 offset:42880
	ds_read_b128 v[58:61], v62 offset:40256
	ds_read_b128 v[62:65], v62 offset:42880
	s_nop 6
	v_cvt_pk_bf16_f32 v66, v66, v67
	v_mfma_f32_32x32x16_bf16 v[34:49], v[186:189], v[130:133], v[34:49]
	v_cvt_pk_bf16_f32 v67, v68, v69
	v_cvt_pk_bf16_f32 v68, v70, v71
	v_cvt_pk_bf16_f32 v69, v72, v73
	v_cvt_pk_bf16_f32 v70, v74, v75
	v_cvt_pk_bf16_f32 v72, v78, v79
	v_add_u32_e32 v78, 0xc800, v172
	v_lshl_add_u32 v74, v145, 1, v172
	s_waitcnt lgkmcnt(3)
	v_mfma_f32_32x32x16_bf16 v[18:33], v[50:53], v[130:133], v[18:33]
	v_bitop3_b32 v50, v141, 8, 24 bitop3:0x6c
	v_lshl_add_u32 v75, v50, 1, v172
	v_bitop3_b32 v50, v141, 16, 24 bitop3:0x6c
	v_lshl_add_u32 v145, v50, 1, v172
	ds_read2_b64 v[50:53], v78 offset0:248 offset1:250
	v_cvt_pk_bf16_f32 v71, v76, v77
	v_cvt_pk_bf16_f32 v73, v80, v81
	v_mfma_f32_32x32x16_bf16 v[34:49], v[190:193], v[126:129], v[34:49]
	s_waitcnt lgkmcnt(0)
	v_mfma_f32_32x32x16_bf16 v[34:49], v[50:53], v[66:69], v[34:49]
	v_mfma_f32_32x32x16_bf16 v[18:33], v[58:61], v[126:129], v[18:33]
	v_bitop3_b32 v58, v141, 24, v141 bitop3:0xc
	v_lshl_add_u32 v141, v58, 1, v172
	ds_read_b64 v[58:59], v74 offset:35072
	ds_read_b64 v[60:61], v75 offset:35072
	ds_read_b64 v[76:77], v75 offset:37696
	ds_read_b64 v[74:75], v74 offset:37696
	ds_read2_b64 v[78:81], v78 offset0:252 offset1:254
	ds_read_b64 v[50:51], v145 offset:35072
	ds_read_b64 v[52:53], v141 offset:35072
	ds_read_b64 v[174:175], v141 offset:37696
	ds_read_b64 v[172:173], v145 offset:37696
	v_xor_b32_e32 v141, 31, v0
	v_cndmask_b32_e64 v141, v141, v0, s[10:11]
	v_mov_b32_e32 v145, v1
	s_waitcnt lgkmcnt(4)
	v_mfma_f32_32x32x16_bf16 v[34:49], v[78:81], v[70:73], v[34:49]
	v_or_b32_e32 v78, s12, v141
	v_lshl_add_u32 v78, v78, 12, v144
	s_movk_i32 s13, 0x1000
	s_and_b64 vcc, exec, s[10:11]
	s_cselect_b32 s13, s13, 0xfffff000
	v_mfma_f32_32x32x16_bf16 v[2:17], v[54:57], v[130:133], v[2:17]
	s_cbranch_vccnz .Lys_fwd
	s_nop 6
	global_atomic_add_f32 v78, v34, s[56:57]
	v_mad_i32_i24 v80, s13, 1, v78
	global_atomic_add_f32 v80, v35, s[56:57]
	v_mad_i32_i24 v81, s13, 2, v78
	global_atomic_add_f32 v81, v36, s[56:57]
	v_mad_i32_i24 v79, s13, 3, v78
	global_atomic_add_f32 v79, v37, s[56:57]
	v_mad_i32_i24 v80, s13, 8, v78
	global_atomic_add_f32 v80, v38, s[56:57]
	v_mad_i32_i24 v81, s13, 9, v78
	global_atomic_add_f32 v81, v39, s[56:57]
	v_mad_i32_i24 v79, s13, 10, v78
	global_atomic_add_f32 v79, v40, s[56:57]
	v_mad_i32_i24 v80, s13, 11, v78
	global_atomic_add_f32 v80, v41, s[56:57]
	v_mad_i32_i24 v81, s13, 16, v78
	global_atomic_add_f32 v81, v42, s[56:57]
	v_mad_i32_i24 v79, s13, 17, v78
	global_atomic_add_f32 v79, v43, s[56:57]
	v_mad_i32_i24 v80, s13, 18, v78
	global_atomic_add_f32 v80, v44, s[56:57]
	v_mad_i32_i24 v81, s13, 19, v78
	global_atomic_add_f32 v81, v45, s[56:57]
	v_mad_i32_i24 v79, s13, 24, v78
	global_atomic_add_f32 v79, v46, s[56:57]
	v_mad_i32_i24 v80, s13, 25, v78
	global_atomic_add_f32 v80, v47, s[56:57]
	v_mad_i32_i24 v81, s13, 26, v78
	global_atomic_add_f32 v81, v48, s[56:57]
	v_mad_i32_i24 v79, s13, 27, v78
	global_atomic_add_f32 v79, v49, s[56:57]
	s_branch .Lys_join
.Lys_fwd:
	s_nop 6
	global_store_dword v78, v34, s[56:57]
	v_mad_i32_i24 v80, s13, 1, v78
	global_store_dword v80, v35, s[56:57]
	v_mad_i32_i24 v81, s13, 2, v78
	global_store_dword v81, v36, s[56:57]
	v_mad_i32_i24 v79, s13, 3, v78
	global_store_dword v79, v37, s[56:57]
	v_mad_i32_i24 v80, s13, 8, v78
	global_store_dword v80, v38, s[56:57]
	v_mad_i32_i24 v81, s13, 9, v78
	global_store_dword v81, v39, s[56:57]
	v_mad_i32_i24 v79, s13, 10, v78
	global_store_dword v79, v40, s[56:57]
	v_mad_i32_i24 v80, s13, 11, v78
	global_store_dword v80, v41, s[56:57]
	v_mad_i32_i24 v81, s13, 16, v78
	global_store_dword v81, v42, s[56:57]
	v_mad_i32_i24 v79, s13, 17, v78
	global_store_dword v79, v43, s[56:57]
	v_mad_i32_i24 v80, s13, 18, v78
	global_store_dword v80, v44, s[56:57]
	v_mad_i32_i24 v81, s13, 19, v78
	global_store_dword v81, v45, s[56:57]
	v_mad_i32_i24 v79, s13, 24, v78
	global_store_dword v79, v46, s[56:57]
	v_mad_i32_i24 v80, s13, 25, v78
	global_store_dword v80, v47, s[56:57]
	v_mad_i32_i24 v81, s13, 26, v78
	global_store_dword v81, v48, s[56:57]
	v_mad_i32_i24 v79, s13, 27, v78
	global_store_dword v79, v49, s[56:57]

.Le23_skip_c:
	s_waitcnt lgkmcnt(0)
	s_barrier
	s_andn2_b64 vcc, exec, s[8:9]
	s_cbranch_vccnz .LBB0_1235
	v_lshlrev_b32_e32 v80, 1, v0
	v_add_u32_e32 v46, v66, v80
	v_add_u32_e32 v47, 0x4000, v46
	ds_read2_b64 v[34:37], v47 offset0:32 offset1:34
	v_cvt_pk_bf16_f32 v38, v18, v19
	v_cvt_pk_bf16_f32 v39, v20, v21
	v_cvt_pk_bf16_f32 v40, v22, v23
	v_cvt_pk_bf16_f32 v41, v24, v25
	ds_read2_b64 v[42:45], v47 offset0:36 offset1:38
	v_lshlrev_b32_e32 v48, 3, v51
	v_cvt_pk_bf16_f32 v72, v26, v27
	v_cvt_pk_bf16_f32 v73, v28, v29
	s_waitcnt lgkmcnt(1)
	v_mfma_f32_32x32x16_bf16 v[50:65], v[34:37], v[38:41], 0
	v_cvt_pk_bf16_f32 v74, v30, v31
	v_cvt_pk_bf16_f32 v75, v32, v33
	ds_read2_b64 v[34:37], v47 offset0:40 offset1:42
	v_cvt_pk_bf16_f32 v76, v2, v3
	v_cvt_pk_bf16_f32 v77, v4, v5
	v_cvt_pk_bf16_f32 v78, v6, v7
	v_cvt_pk_bf16_f32 v79, v8, v9
	s_waitcnt lgkmcnt(1)
	v_mfma_f32_32x32x16_bf16 v[50:65], v[42:45], v[72:75], v[50:65]
	ds_read2_b64 v[42:45], v47 offset0:44 offset1:46
	v_cvt_pk_bf16_f32 v172, v10, v11
	v_cvt_pk_bf16_f32 v173, v12, v13
	v_cvt_pk_bf16_f32 v174, v14, v15
	v_cvt_pk_bf16_f32 v175, v16, v17
	v_mov_b32_e32 v49, s88
	v_bitop3_b32 v47, v48, v141, 24 bitop3:0x78
	s_waitcnt lgkmcnt(1)
	v_mfma_f32_32x32x16_bf16 v[50:65], v[34:37], v[76:79], v[50:65]
	v_lshlrev_b32_e32 v34, 6, v70
	v_sub_u32_e32 v177, v66, v34
	v_lshl_add_u32 v70, v48, 1, v177
	ds_read_b128 v[34:37], v70 offset:50624
	v_mad_u32_u24 v49, v71, s77, v49
	v_lshlrev_b32_e32 v207, 1, v47
	v_and_b32_e32 v145, 24, v141
	s_waitcnt lgkmcnt(1)
	v_mfma_f32_32x32x16_bf16 v[50:65], v[42:45], v[172:175], v[50:65]
	v_add_u32_e32 v42, v49, v207
	ds_read_b128 v[130:133], v42 offset:45440
	v_bitop3_b32 v67, v48, v145, 16 bitop3:0x36
	v_lshlrev_b32_e32 v212, 1, v67
	v_add_u32_e32 v71, 0x5000, v46
	v_add_u32_e32 v47, v49, v212
	ds_read_b128 v[42:45], v70 offset:50656
	ds_read_b128 v[126:129], v47 offset:45440
	s_waitcnt lgkmcnt(2)
	v_mfma_f32_32x32x16_bf16 v[50:65], v[34:37], v[130:133], v[50:65]
	ds_read2_b64 v[34:37], v71 offset0:96 offset1:98
	ds_read2_b64 v[66:69], v71 offset0:100 offset1:102
	ds_read2_b64 v[178:181], v71 offset0:104 offset1:106
	ds_read2_b64 v[182:185], v71 offset0:108 offset1:110
	ds_read_b128 v[186:189], v70 offset:55744
	ds_read_b128 v[190:193], v70 offset:55776
	v_lshlrev_b32_e32 v81, 2, v0
	s_add_i32 s58, s89, 32
	s_and_b64 s[12:13], s[10:11], exec
	s_cselect_b32 s12, s91, s58
	s_waitcnt lgkmcnt(6)
	v_mfma_f32_32x32x16_bf16 v[50:65], v[42:45], v[126:129], v[50:65]
	s_add_i32 s12, s12, s83
	s_waitcnt lgkmcnt(5)
	v_mfma_f32_32x32x16_bf16 v[34:49], v[34:37], v[38:41], 0
	s_nop 8
	v_cvt_pk_bf16_f32 v50, v50, v51
	v_cvt_pk_bf16_f32 v51, v52, v53
	v_cvt_pk_bf16_f32 v52, v54, v55
	v_cvt_pk_bf16_f32 v53, v56, v57
	s_waitcnt lgkmcnt(4)
	v_mfma_f32_32x32x16_bf16 v[34:49], v[66:69], v[72:75], v[34:49]
	ds_read_b128 v[66:69], v81 offset:60928
	ds_read_b128 v[70:73], v81 offset:60960
	ds_read_b128 v[194:197], v81 offset:60864
	ds_read_b128 v[198:201], v81 offset:60896
	ds_read_b128 v[202:205], v81 offset:60992
	ds_read_b128 v[208:211], v81 offset:61024
	s_waitcnt lgkmcnt(4)
	v_pk_mul_f32 v[30:31], v[30:31], v[70:71]
	v_pk_mul_f32 v[26:27], v[26:27], v[66:67]
	v_pk_mul_f32 v[32:33], v[32:33], v[72:73]
	v_pk_mul_f32 v[28:29], v[28:29], v[68:69]
	ds_read_b128 v[66:69], v81 offset:61056
	ds_read_b128 v[70:73], v81 offset:61088
	s_waitcnt lgkmcnt(4)
	v_pk_mul_f32 v[22:23], v[22:23], v[198:199]
	v_mfma_f32_32x32x16_bf16 v[34:49], v[178:181], v[76:79], v[34:49]
	v_mul_f32_e64 v24, v24, v200
	v_mul_f32_e64 v25, v25, v201
	s_waitcnt lgkmcnt(1)
	v_mul_f32_e64 v10, v10, v66
	v_mul_f32_e64 v11, v11, v67
	s_waitcnt lgkmcnt(0)
	v_pk_mul_f32 v[14:15], v[14:15], v[70:71]
	v_pk_mul_f32 v[16:17], v[16:17], v[72:73]
	v_pk_mul_f32 v[12:13], v[12:13], v[68:69]
	v_pk_mul_f32 v[20:21], v[20:21], v[196:197]
	v_pk_mul_f32 v[18:19], v[18:19], v[194:195]
	v_mfma_f32_32x32x16_bf16 v[34:49], v[182:185], v[172:175], v[34:49]
	v_add_u32_e32 v172, v177, v80
	v_add_u32_e32 v66, 0xe000, v172
	ds_read2_b64 v[74:77], v66 offset0:120 offset1:122
	ds_read2_b64 v[54:57], v66 offset0:124 offset1:126
	v_mul_f32_e64 v6, v6, v208
	v_mul_f32_e64 v7, v7, v209
	v_pk_mul_f32 v[8:9], v[8:9], v[210:211]
	v_pk_mul_f32 v[4:5], v[4:5], v[204:205]
	s_waitcnt lgkmcnt(1)
	v_mfma_f32_32x32x16_bf16 v[66:81], v[74:77], v[50:53], 0
	v_cvt_pk_bf16_f32 v50, v58, v59
	v_cvt_pk_bf16_f32 v51, v60, v61
	v_cvt_pk_bf16_f32 v52, v62, v63
	v_cvt_pk_bf16_f32 v53, v64, v65
	v_add_u32_e32 v62, v177, v212
	v_pk_mul_f32 v[2:3], v[2:3], v[202:203]
	s_waitcnt lgkmcnt(0)
	v_mfma_f32_32x32x16_bf16 v[66:81], v[54:57], v[50:53], v[66:81]
	v_add_u32_e32 v54, v177, v207
	ds_read_b128 v[50:53], v54 offset:40256
	ds_read_b128 v[54:57], v54 offset:42880
	ds_read_b128 v[58:61], v62 offset:40256
	ds_read_b128 v[62:65], v62 offset:42880
	s_nop 6
	v_cvt_pk_bf16_f32 v66, v66, v67
	v_mfma_f32_32x32x16_bf16 v[34:49], v[186:189], v[130:133], v[34:49]
	v_cvt_pk_bf16_f32 v67, v68, v69
	v_cvt_pk_bf16_f32 v68, v70, v71
	v_cvt_pk_bf16_f32 v69, v72, v73
	v_cvt_pk_bf16_f32 v70, v74, v75
	v_cvt_pk_bf16_f32 v72, v78, v79
	v_add_u32_e32 v78, 0xc800, v172
	v_lshl_add_u32 v74, v145, 1, v172
	s_waitcnt lgkmcnt(3)
	v_mfma_f32_32x32x16_bf16 v[18:33], v[50:53], v[130:133], v[18:33]
	v_bitop3_b32 v50, v141, 8, 24 bitop3:0x6c
	v_lshl_add_u32 v75, v50, 1, v172
	v_bitop3_b32 v50, v141, 16, 24 bitop3:0x6c
	v_lshl_add_u32 v145, v50, 1, v172
	ds_read2_b64 v[50:53], v78 offset0:248 offset1:250
	v_cvt_pk_bf16_f32 v71, v76, v77
	v_cvt_pk_bf16_f32 v73, v80, v81
	v_mfma_f32_32x32x16_bf16 v[34:49], v[190:193], v[126:129], v[34:49]
	s_waitcnt lgkmcnt(0)
	v_mfma_f32_32x32x16_bf16 v[34:49], v[50:53], v[66:69], v[34:49]
	v_mfma_f32_32x32x16_bf16 v[18:33], v[58:61], v[126:129], v[18:33]
	v_bitop3_b32 v58, v141, 24, v141 bitop3:0xc
	v_lshl_add_u32 v141, v58, 1, v172
	ds_read_b64 v[58:59], v74 offset:35072
	ds_read_b64 v[60:61], v75 offset:35072
	ds_read_b64 v[76:77], v75 offset:37696
	ds_read_b64 v[74:75], v74 offset:37696
	ds_read2_b64 v[78:81], v78 offset0:252 offset1:254
	ds_read_b64 v[50:51], v145 offset:35072
	ds_read_b64 v[52:53], v141 offset:35072
	ds_read_b64 v[174:175], v141 offset:37696
	ds_read_b64 v[172:173], v145 offset:37696
	v_xor_b32_e32 v141, 31, v0
	v_cndmask_b32_e64 v141, v141, v0, s[10:11]
	s_waitcnt lgkmcnt(4)
	v_mfma_f32_32x32x16_bf16 v[34:49], v[78:81], v[70:73], v[34:49]
	v_or_b32_e32 v78, s12, v141
	v_lshl_add_u32 v78, v78, 12, v144
	s_movk_i32 s13, 0x1000
	s_and_b64 vcc, exec, s[10:11]
	s_cselect_b32 s13, s13, 0xfffff000
	v_mfma_f32_32x32x16_bf16 v[2:17], v[54:57], v[130:133], v[2:17]
	s_nop 6
	global_atomic_add_f32 v78, v34, s[56:57]
	v_mad_i32_i24 v80, s13, 1, v78
	global_atomic_add_f32 v80, v35, s[56:57]
	v_mad_i32_i24 v81, s13, 2, v78
	global_atomic_add_f32 v81, v36, s[56:57]
	v_mad_i32_i24 v79, s13, 3, v78
	global_atomic_add_f32 v79, v37, s[56:57]
	v_mad_i32_i24 v80, s13, 8, v78
	global_atomic_add_f32 v80, v38, s[56:57]
	v_mad_i32_i24 v81, s13, 9, v78
	global_atomic_add_f32 v81, v39, s[56:57]
	v_mad_i32_i24 v79, s13, 10, v78
	global_atomic_add_f32 v79, v40, s[56:57]
	v_mad_i32_i24 v80, s13, 11, v78
	global_atomic_add_f32 v80, v41, s[56:57]
	v_mad_i32_i24 v81, s13, 16, v78
	global_atomic_add_f32 v81, v42, s[56:57]
	v_mad_i32_i24 v79, s13, 17, v78
	global_atomic_add_f32 v79, v43, s[56:57]
	v_mad_i32_i24 v80, s13, 18, v78
	global_atomic_add_f32 v80, v44, s[56:57]
	v_mad_i32_i24 v81, s13, 19, v78
	global_atomic_add_f32 v81, v45, s[56:57]
	v_mad_i32_i24 v79, s13, 24, v78
	global_atomic_add_f32 v79, v46, s[56:57]
	v_mad_i32_i24 v80, s13, 25, v78
	global_atomic_add_f32 v80, v47, s[56:57]
	v_mad_i32_i24 v81, s13, 26, v78
	global_atomic_add_f32 v81, v48, s[56:57]
	v_mad_i32_i24 v79, s13, 27, v78
	global_atomic_add_f32 v79, v49, s[56:57]
	v_mfma_f32_32x32x16_bf16 v[2:17], v[62:65], v[126:129], v[2:17]
	v_mfma_f32_32x32x16_bf16 v[18:33], v[58:61], v[66:69], v[18:33]
	v_mfma_f32_32x32x16_bf16 v[2:17], v[74:77], v[66:69], v[2:17]
	s_waitcnt lgkmcnt(2)
	v_mfma_f32_32x32x16_bf16 v[18:33], v[50:53], v[70:73], v[18:33]
	s_waitcnt lgkmcnt(0)
	v_mfma_f32_32x32x16_bf16 v[2:17], v[172:175], v[70:73], v[2:17]
	s_branch .LBB0_1235
